# NA main-pair loop (G==256 path) rewritten by hand: saddr loads, on-the-fly window masks, permlane max, ~45% fewer instructions (on top of v11)
# speedup vs baseline: 1.0064x; 1.0011x over previous
.LBB0_758:
	s_waitcnt vmcnt(0)
	v_readfirstlane_b32 s42, v188
	v_readfirstlane_b32 s43, v189
	v_readfirstlane_b32 s44, v190
	v_readfirstlane_b32 s45, v191
	v_readlane_b32 s0, v253, 34
	v_readlane_b32 s1, v251, 25
	v_readlane_b32 s13, v252, 14
	s_nop 3
	v_subrev_u32_e32 v174, s42, v188
	v_subrev_u32_e32 v175, s44, v190
	v_add_u32_e32 v176, 0x42000, v175
	v_add_u32_e32 v177, 0x84000, v175
	v_add_u32_e32 v178, 0xc6000, v175
	v_or_b32_e32 v3, s0, v187
	v_max_u32_e32 v3, 8, v3
	v_add_u32_e32 v3, -8, v3
	v_sub_u32_e32 v128, v180, v3
	v_add_u32_e32 v129, 32, v128
	v_or_b32_e32 v3, s1, v187
	v_add_u32_e32 v3, -8, v3
	v_min_u32_e32 v3, 48, v3
	v_sub_u32_e32 v130, v180, v3
	v_add_u32_e32 v131, 32, v130
	v_add_lshl_u32 v240, v233, v180, 2
	v_add_lshl_u32 v241, v231, v180, 2
	v_add_u32_e32 v240, 0x1e000, v240
	v_add_u32_e32 v241, 0x1e000, v241
	v_mov_b32_e32 v243, 0xff800000
	s_mov_b32 s12, 0
.Lna_loop:
	s_add_i32 vcc_hi, s62, s12
	s_cmp_lt_u32 s12, 4
	s_cselect_b32 vcc_lo, s12, vcc_hi
	s_lshl_b32 vcc_lo, vcc_lo, 6
	s_or_b32 s14, vcc_lo, 32
	s_lshl_b32 s14, s14, 9
	s_add_u32 s0, s42, s14
	s_addc_u32 s1, s43, 0
	global_load_dwordx4 v[112:115], v174, s[0:1]
	global_load_dwordx4 v[116:119], v174, s[0:1] offset:2048
	global_load_dwordx4 v[120:123], v174, s[0:1] offset:64
	global_load_dwordx4 v[124:127], v174, s[0:1] offset:2112
	s_lshl_b32 s14, vcc_lo, 1
	s_add_i32 s14, s14, 64
	s_add_u32 s0, s44, s14
	s_addc_u32 s1, s45, 0
	global_load_dwordx4 v[80:83], v175, s[0:1]
	global_load_dwordx4 v[84:87], v176, s[0:1]
	global_load_dwordx4 v[88:91], v177, s[0:1]
	global_load_dwordx4 v[92:95], v178, s[0:1]
	s_waitcnt vmcnt(8)
	v_mfma_f32_16x16x32_bf16 v[148:151], v[96:99], v[36:39], 0
	v_mfma_f32_16x16x32_bf16 v[152:155], v[100:103], v[36:39], 0
	v_mfma_f32_16x16x32_bf16 v[148:151], v[104:107], v[48:51], v[148:151]
	v_mfma_f32_16x16x32_bf16 v[152:155], v[108:111], v[48:51], v[152:155]
	s_cmp_gt_u32 s12, 3
	s_cbranch_scc0 .Lna_nowin_c1
	ds_read2_b32 v[156:157], v240 offset0:0 offset1:1
	ds_read2_b32 v[158:159], v240 offset0:2 offset1:3
	ds_read2_b32 v[160:161], v240 offset0:4 offset1:5
	ds_read2_b32 v[162:163], v240 offset0:6 offset1:7
	s_nop 3
	s_waitcnt lgkmcnt(0)
	v_add_u32_e32 v3, 0, v128
	v_add_f32_e32 v179, v148, v156
	v_cmp_gt_u32_e32 vcc, 16, v3
	v_add_u32_e32 v172, 1, v128
	v_add_f32_e32 v235, v149, v157
	v_cndmask_b32_e32 v148, v243, v179, vcc
	v_cmp_gt_u32_e32 vcc, 16, v172
	v_add_u32_e32 v3, 2, v128
	v_add_f32_e32 v179, v150, v158
	v_cndmask_b32_e32 v149, v243, v235, vcc
	v_cmp_gt_u32_e32 vcc, 16, v3
	v_add_u32_e32 v172, 3, v128
	v_add_f32_e32 v235, v151, v159
	v_cndmask_b32_e32 v150, v243, v179, vcc
	v_cmp_gt_u32_e32 vcc, 16, v172
	v_add_u32_e32 v3, 4, v128
	v_add_f32_e32 v179, v152, v160
	v_cndmask_b32_e32 v151, v243, v235, vcc
	v_cmp_gt_u32_e32 vcc, 16, v3
	v_add_u32_e32 v172, 5, v128
	v_add_f32_e32 v235, v153, v161
	v_cndmask_b32_e32 v152, v243, v179, vcc
	v_cmp_gt_u32_e32 vcc, 16, v172
	v_add_u32_e32 v3, 6, v128
	v_add_f32_e32 v179, v154, v162
	v_cndmask_b32_e32 v153, v243, v235, vcc
	v_cmp_gt_u32_e32 vcc, 16, v3
	v_add_u32_e32 v172, 7, v128
	v_add_f32_e32 v235, v155, v163
	v_cndmask_b32_e32 v154, v243, v179, vcc
	v_cmp_gt_u32_e32 vcc, 16, v172
	s_nop 1
	v_cndmask_b32_e32 v155, v243, v235, vcc
	s_branch .Lna_sm_c1
.Lna_nowin_c1:
	s_nop 7
.Lna_sm_c1:
	v_max3_f32 v3, v148, v149, v150
	v_max3_f32 v172, v151, v152, v153
	v_max3_f32 v3, v3, v154, v155
	v_max_f32_e32 v3, v3, v172
	v_mov_b32_e32 v172, v3
	s_nop 1
	v_permlane16_swap_b32_e32 v3, v172
	v_max_f32_e32 v3, v3, v172
	v_mov_b32_e32 v172, v3
	s_nop 1
	v_permlane32_swap_b32_e32 v3, v172
	v_max3_f32 v3, v173, v3, v172
	v_sub_f32_e32 v0, v173, v3
	v_exp_f32_e32 v0, v0
	v_mov_b32_e32 v173, v3
	v_sub_f32_e32 v148, v148, v3
	v_sub_f32_e32 v149, v149, v3
	v_sub_f32_e32 v150, v150, v3
	v_sub_f32_e32 v151, v151, v3
	v_sub_f32_e32 v152, v152, v3
	v_sub_f32_e32 v153, v153, v3
	v_sub_f32_e32 v154, v154, v3
	v_sub_f32_e32 v155, v155, v3
	v_exp_f32_e32 v148, v148
	v_exp_f32_e32 v149, v149
	v_exp_f32_e32 v150, v150
	v_exp_f32_e32 v151, v151
	v_exp_f32_e32 v152, v152
	v_exp_f32_e32 v153, v153
	v_exp_f32_e32 v154, v154
	v_exp_f32_e32 v155, v155
	v_cmp_neq_f32_e32 vcc, 1.0, v0
	v_add_f32_e32 v172, v148, v149
	v_add_f32_e32 v179, v150, v151
	v_add_f32_e32 v235, v152, v153
	v_add_f32_e32 v242, v154, v155
	v_add_f32_e32 v172, v172, v179
	v_add_f32_e32 v235, v235, v242
	v_add_f32_e32 v172, v172, v235
	v_fma_f32 v234, v234, v0, v172
	v_cvt_pk_bf16_f32 v168, v148, v149
	v_cvt_pk_bf16_f32 v169, v150, v151
	v_cvt_pk_bf16_f32 v170, v152, v153
	v_cvt_pk_bf16_f32 v171, v154, v155
	s_cbranch_vccz .Lna_nors_c1
	v_mul_f32_e32 v144, v0, v144
	v_mul_f32_e32 v145, v0, v145
	v_mul_f32_e32 v146, v0, v146
	v_mul_f32_e32 v147, v0, v147
	v_mul_f32_e32 v132, v0, v132
	v_mul_f32_e32 v133, v0, v133
	v_mul_f32_e32 v134, v0, v134
	v_mul_f32_e32 v135, v0, v135
	v_mul_f32_e32 v136, v0, v136
	v_mul_f32_e32 v137, v0, v137
	v_mul_f32_e32 v138, v0, v138
	v_mul_f32_e32 v139, v0, v139
	v_mul_f32_e32 v140, v0, v140
	v_mul_f32_e32 v141, v0, v141
	v_mul_f32_e32 v142, v0, v142
	v_mul_f32_e32 v143, v0, v143
.Lna_nors_c1:
	s_nop 1
	v_mfma_f32_16x16x32_bf16 v[144:147], v[68:71], v[168:171], v[144:147]
	v_mfma_f32_16x16x32_bf16 v[132:135], v[76:79], v[168:171], v[132:135]
	v_mfma_f32_16x16x32_bf16 v[136:139], v[64:67], v[168:171], v[136:139]
	v_mfma_f32_16x16x32_bf16 v[140:143], v[72:75], v[168:171], v[140:143]
	s_cmp_gt_u32 s12, 3
	s_cselect_b32 s14, s13, 0
	s_cmp_lg_u32 s14, 0
	s_cbranch_scc1 .Lna_skip_c2
	v_mfma_f32_16x16x32_bf16 v[148:151], v[96:99], v[44:47], 0
	v_mfma_f32_16x16x32_bf16 v[152:155], v[100:103], v[44:47], 0
	v_mfma_f32_16x16x32_bf16 v[148:151], v[104:107], v[40:43], v[148:151]
	v_mfma_f32_16x16x32_bf16 v[152:155], v[108:111], v[40:43], v[152:155]
	s_cmp_gt_u32 s12, 3
	s_cbranch_scc0 .Lna_nowin_c2
	ds_read2_b32 v[156:157], v241 offset0:0 offset1:1
	ds_read2_b32 v[158:159], v241 offset0:2 offset1:3
	ds_read2_b32 v[160:161], v241 offset0:4 offset1:5
	ds_read2_b32 v[162:163], v241 offset0:6 offset1:7
	s_nop 3
	s_waitcnt lgkmcnt(0)
	v_add_u32_e32 v3, 0, v130
	v_add_f32_e32 v179, v148, v156
	v_cmp_gt_u32_e32 vcc, 16, v3
	v_add_u32_e32 v172, 1, v130
	v_add_f32_e32 v235, v149, v157
	v_cndmask_b32_e32 v148, v243, v179, vcc
	v_cmp_gt_u32_e32 vcc, 16, v172
	v_add_u32_e32 v3, 2, v130
	v_add_f32_e32 v179, v150, v158
	v_cndmask_b32_e32 v149, v243, v235, vcc
	v_cmp_gt_u32_e32 vcc, 16, v3
	v_add_u32_e32 v172, 3, v130
	v_add_f32_e32 v235, v151, v159
	v_cndmask_b32_e32 v150, v243, v179, vcc
	v_cmp_gt_u32_e32 vcc, 16, v172
	v_add_u32_e32 v3, 4, v130
	v_add_f32_e32 v179, v152, v160
	v_cndmask_b32_e32 v151, v243, v235, vcc
	v_cmp_gt_u32_e32 vcc, 16, v3
	v_add_u32_e32 v172, 5, v130
	v_add_f32_e32 v235, v153, v161
	v_cndmask_b32_e32 v152, v243, v179, vcc
	v_cmp_gt_u32_e32 vcc, 16, v172
	v_add_u32_e32 v3, 6, v130
	v_add_f32_e32 v179, v154, v162
	v_cndmask_b32_e32 v153, v243, v235, vcc
	v_cmp_gt_u32_e32 vcc, 16, v3
	v_add_u32_e32 v172, 7, v130
	v_add_f32_e32 v235, v155, v163
	v_cndmask_b32_e32 v154, v243, v179, vcc
	v_cmp_gt_u32_e32 vcc, 16, v172
	s_nop 1
	v_cndmask_b32_e32 v155, v243, v235, vcc
	s_branch .Lna_sm_c2

.Lna_sm_c2:
	v_max3_f32 v3, v148, v149, v150
	v_max3_f32 v172, v151, v152, v153
	v_max3_f32 v3, v3, v154, v155
	v_max_f32_e32 v3, v3, v172
	v_mov_b32_e32 v172, v3
	s_nop 1
	v_permlane16_swap_b32_e32 v3, v172
	v_max_f32_e32 v3, v3, v172
	v_mov_b32_e32 v172, v3
	s_nop 1
	v_permlane32_swap_b32_e32 v3, v172
	v_max3_f32 v3, v2, v3, v172
	v_sub_f32_e32 v0, v2, v3
	v_exp_f32_e32 v0, v0
	v_mov_b32_e32 v2, v3
	v_sub_f32_e32 v148, v148, v3
	v_sub_f32_e32 v149, v149, v3
	v_sub_f32_e32 v150, v150, v3
	v_sub_f32_e32 v151, v151, v3
	v_sub_f32_e32 v152, v152, v3
	v_sub_f32_e32 v153, v153, v3
	v_sub_f32_e32 v154, v154, v3
	v_sub_f32_e32 v155, v155, v3
	v_exp_f32_e32 v148, v148
	v_exp_f32_e32 v149, v149
	v_exp_f32_e32 v150, v150
	v_exp_f32_e32 v151, v151
	v_exp_f32_e32 v152, v152
	v_exp_f32_e32 v153, v153
	v_exp_f32_e32 v154, v154
	v_exp_f32_e32 v155, v155
	v_cmp_neq_f32_e32 vcc, 1.0, v0
	v_add_f32_e32 v172, v148, v149
	v_add_f32_e32 v179, v150, v151
	v_add_f32_e32 v235, v152, v153
	v_add_f32_e32 v242, v154, v155
	v_add_f32_e32 v172, v172, v179
	v_add_f32_e32 v235, v235, v242
	v_add_f32_e32 v172, v172, v235
	v_fma_f32 v232, v232, v0, v172
	v_cvt_pk_bf16_f32 v168, v148, v149
	v_cvt_pk_bf16_f32 v169, v150, v151
	v_cvt_pk_bf16_f32 v170, v152, v153
	v_cvt_pk_bf16_f32 v171, v154, v155
	s_cbranch_vccz .Lna_nors_c2
	v_mul_f32_e32 v52, v0, v52
	v_mul_f32_e32 v53, v0, v53
	v_mul_f32_e32 v54, v0, v54
	v_mul_f32_e32 v55, v0, v55
	v_mul_f32_e32 v56, v0, v56
	v_mul_f32_e32 v57, v0, v57
	v_mul_f32_e32 v58, v0, v58
	v_mul_f32_e32 v59, v0, v59
	v_mul_f32_e32 v60, v0, v60
	v_mul_f32_e32 v61, v0, v61
	v_mul_f32_e32 v62, v0, v62
	v_mul_f32_e32 v63, v0, v63
	v_mul_f32_e32 v164, v0, v164
	v_mul_f32_e32 v165, v0, v165
	v_mul_f32_e32 v166, v0, v166
	v_mul_f32_e32 v167, v0, v167
.Lna_nors_c2:
	s_nop 1
	v_mfma_f32_16x16x32_bf16 v[52:55], v[68:71], v[168:171], v[52:55]
	v_mfma_f32_16x16x32_bf16 v[56:59], v[76:79], v[168:171], v[56:59]
	v_mfma_f32_16x16x32_bf16 v[60:63], v[64:67], v[168:171], v[60:63]
	v_mfma_f32_16x16x32_bf16 v[164:167], v[72:75], v[168:171], v[164:167]
.Lna_skip_c2:
	v_readlane_b32 s14, v252, 23
	s_nop 3
	s_add_i32 s14, s14, -1
	s_add_i32 s0, s12, 1
	s_min_u32 s14, s0, s14
	s_add_i32 vcc_hi, s62, s14
	s_cmp_lt_u32 s14, 4
	s_cselect_b32 vcc_lo, s14, vcc_hi
	s_lshl_b32 vcc_lo, vcc_lo, 6
	s_mov_b32 s14, vcc_lo
	s_lshl_b32 s14, s14, 9
	s_add_u32 s0, s42, s14
	s_addc_u32 s1, s43, 0
	global_load_dwordx4 v[96:99], v174, s[0:1]
	global_load_dwordx4 v[100:103], v174, s[0:1] offset:2048
	global_load_dwordx4 v[104:107], v174, s[0:1] offset:64
	global_load_dwordx4 v[108:111], v174, s[0:1] offset:2112
	s_lshl_b32 s14, vcc_lo, 1
	s_add_u32 s0, s44, s14
	s_addc_u32 s1, s45, 0
	global_load_dwordx4 v[68:71], v175, s[0:1]
	global_load_dwordx4 v[76:79], v176, s[0:1]
	global_load_dwordx4 v[64:67], v177, s[0:1]
	global_load_dwordx4 v[72:75], v178, s[0:1]
	s_waitcnt vmcnt(8)
	s_cmp_gt_u32 s12, 3
	s_cselect_b32 s14, 1, 0
	s_cmp_eq_u32 s13, 0
	s_cselect_b32 s0, 1, 0
	s_and_b32 s14, s14, s0
	s_cmp_lg_u32 s14, 0
	s_cbranch_scc1 .Lna_skip_c3
	v_mfma_f32_16x16x32_bf16 v[148:151], v[112:115], v[36:39], 0
	v_mfma_f32_16x16x32_bf16 v[152:155], v[116:119], v[36:39], 0
	v_mfma_f32_16x16x32_bf16 v[148:151], v[120:123], v[48:51], v[148:151]
	v_mfma_f32_16x16x32_bf16 v[152:155], v[124:127], v[48:51], v[152:155]
	s_cmp_gt_u32 s12, 3
	s_cbranch_scc0 .Lna_nowin_c3
	ds_read2_b32 v[156:157], v240 offset0:32 offset1:33
	ds_read2_b32 v[158:159], v240 offset0:34 offset1:35
	ds_read2_b32 v[160:161], v240 offset0:36 offset1:37
	ds_read2_b32 v[162:163], v240 offset0:38 offset1:39
	s_nop 3
	s_waitcnt lgkmcnt(0)
	v_add_u32_e32 v3, 0, v129
	v_add_f32_e32 v179, v148, v156
	v_cmp_gt_u32_e32 vcc, 16, v3
	v_add_u32_e32 v172, 1, v129
	v_add_f32_e32 v235, v149, v157
	v_cndmask_b32_e32 v148, v243, v179, vcc
	v_cmp_gt_u32_e32 vcc, 16, v172
	v_add_u32_e32 v3, 2, v129
	v_add_f32_e32 v179, v150, v158
	v_cndmask_b32_e32 v149, v243, v235, vcc
	v_cmp_gt_u32_e32 vcc, 16, v3
	v_add_u32_e32 v172, 3, v129
	v_add_f32_e32 v235, v151, v159
	v_cndmask_b32_e32 v150, v243, v179, vcc
	v_cmp_gt_u32_e32 vcc, 16, v172
	v_add_u32_e32 v3, 4, v129
	v_add_f32_e32 v179, v152, v160
	v_cndmask_b32_e32 v151, v243, v235, vcc
	v_cmp_gt_u32_e32 vcc, 16, v3
	v_add_u32_e32 v172, 5, v129
	v_add_f32_e32 v235, v153, v161
	v_cndmask_b32_e32 v152, v243, v179, vcc
	v_cmp_gt_u32_e32 vcc, 16, v172
	v_add_u32_e32 v3, 6, v129
	v_add_f32_e32 v179, v154, v162
	v_cndmask_b32_e32 v153, v243, v235, vcc
	v_cmp_gt_u32_e32 vcc, 16, v3
	v_add_u32_e32 v172, 7, v129
	v_add_f32_e32 v235, v155, v163
	v_cndmask_b32_e32 v154, v243, v179, vcc
	v_cmp_gt_u32_e32 vcc, 16, v172
	s_nop 1
	v_cndmask_b32_e32 v155, v243, v235, vcc
	s_branch .Lna_sm_c3

.Lna_nors_c3:
	s_nop 1
	v_mfma_f32_16x16x32_bf16 v[144:147], v[80:83], v[168:171], v[144:147]
	v_mfma_f32_16x16x32_bf16 v[132:135], v[84:87], v[168:171], v[132:135]
	v_mfma_f32_16x16x32_bf16 v[136:139], v[88:91], v[168:171], v[136:139]
	v_mfma_f32_16x16x32_bf16 v[140:143], v[92:95], v[168:171], v[140:143]
.Lna_skip_c3:
	v_mfma_f32_16x16x32_bf16 v[148:151], v[112:115], v[44:47], 0
	v_mfma_f32_16x16x32_bf16 v[152:155], v[116:119], v[44:47], 0
	v_mfma_f32_16x16x32_bf16 v[148:151], v[120:123], v[40:43], v[148:151]
	v_mfma_f32_16x16x32_bf16 v[152:155], v[124:127], v[40:43], v[152:155]
	s_cmp_gt_u32 s12, 3
	s_cbranch_scc0 .Lna_nowin_c4
	ds_read2_b32 v[156:157], v241 offset0:32 offset1:33
	ds_read2_b32 v[158:159], v241 offset0:34 offset1:35
	ds_read2_b32 v[160:161], v241 offset0:36 offset1:37
	ds_read2_b32 v[162:163], v241 offset0:38 offset1:39
	s_nop 3
	s_waitcnt lgkmcnt(0)
	v_add_u32_e32 v3, 0, v131
	v_add_f32_e32 v179, v148, v156
	v_cmp_gt_u32_e32 vcc, 16, v3
	v_add_u32_e32 v172, 1, v131
	v_add_f32_e32 v235, v149, v157
	v_cndmask_b32_e32 v148, v243, v179, vcc
	v_cmp_gt_u32_e32 vcc, 16, v172
	v_add_u32_e32 v3, 2, v131
	v_add_f32_e32 v179, v150, v158
	v_cndmask_b32_e32 v149, v243, v235, vcc
	v_cmp_gt_u32_e32 vcc, 16, v3
	v_add_u32_e32 v172, 3, v131
	v_add_f32_e32 v235, v151, v159
	v_cndmask_b32_e32 v150, v243, v179, vcc
	v_cmp_gt_u32_e32 vcc, 16, v172
	v_add_u32_e32 v3, 4, v131
	v_add_f32_e32 v179, v152, v160
	v_cndmask_b32_e32 v151, v243, v235, vcc
	v_cmp_gt_u32_e32 vcc, 16, v3
	v_add_u32_e32 v172, 5, v131
	v_add_f32_e32 v235, v153, v161
	v_cndmask_b32_e32 v152, v243, v179, vcc
	v_cmp_gt_u32_e32 vcc, 16, v172
	v_add_u32_e32 v3, 6, v131
	v_add_f32_e32 v179, v154, v162
	v_cndmask_b32_e32 v153, v243, v235, vcc
	v_cmp_gt_u32_e32 vcc, 16, v3
	v_add_u32_e32 v172, 7, v131
	v_add_f32_e32 v235, v155, v163
	v_cndmask_b32_e32 v154, v243, v179, vcc
	v_cmp_gt_u32_e32 vcc, 16, v172
	s_nop 1
	v_cndmask_b32_e32 v155, v243, v235, vcc
	s_branch .Lna_sm_c4

.Lna_nors_c4:
	s_nop 1
	v_mfma_f32_16x16x32_bf16 v[52:55], v[80:83], v[168:171], v[52:55]
	v_mfma_f32_16x16x32_bf16 v[56:59], v[84:87], v[168:171], v[56:59]
	v_mfma_f32_16x16x32_bf16 v[60:63], v[88:91], v[168:171], v[60:63]
	v_mfma_f32_16x16x32_bf16 v[164:167], v[92:95], v[168:171], v[164:167]
	v_add_u32_e32 v240, 0x7c, v240
	v_add_u32_e32 v241, 0x7c, v241
	s_add_i32 s12, s12, 1
	v_readlane_b32 s14, v252, 23
	s_nop 3
	s_cmp_lt_u32 s12, s14
	s_cbranch_scc1 .Lna_loop
	s_waitcnt vmcnt(0)
	v_readlane_b32 s90, v254, 8
	v_readlane_b32 s91, v254, 9
	s_mov_b32 s96, 0x1e000
	s_nop 7
